# post phase: half of the workgroups run HGRN chunk-state units before MoBA prep units (swap order to overlap bandwidth- and compute-heavy work)
# baseline (speedup 1.0000x reference)
; #define LAS __attribute__((address_space(3)))
; __device__ __forceinline__ int otid() { int t = threadIdx.x; asm volatile("" : "+v"(t)); return t; }
; __global__ void __launch_bounds__(512) hymba_fwd(Args a) {
;     ...
;             if (bx >= NKV) {
;                 const int wb = bx - NKV, WG = G - NKV;
;                 const int tid = otid();
;                 if (tid < 128) ((LAS float*)(lds + 68608))[tid] = (tid < 64) ? a.mqn[l * 64 + tid] : a.mkn[l * 64 + tid - 64];
;                 if (tid < 512) ((LAS float*)(lds + 106496))[tid] = ((const float*)(a.ws + WS_LB))[l * 512 + tid];
;                 __syncthreads();
.LBB0_419:
	v_readlane_b32 s4, v245, 28
	v_readlane_b32 s5, v245, 29
	s_andn2_b64 vcc, exec, s[4:5]
	s_waitcnt vmcnt(0)
	s_barrier
	s_cbranch_vccnz .LBB0_449
	s_mov_b32 s99, 0
.Lx3_reload:
	v_mov_b32_e32 v96, v178
	s_movk_i32 s4, 0x7f
	s_nop 0
	v_cmp_lt_i32_e64 s[42:43], s4, v96
	s_movk_i32 s4, 0x80
	v_cmp_gt_i32_e32 vcc, s4, v96
	v_lshl_add_u32 v101, v96, 2, 0
	s_and_saveexec_b64 s[14:15], vcc
	s_cbranch_execz .LBB0_422
	v_readlane_b32 s4, v244, 61
	v_cmp_gt_i32_e32 vcc, 64, v96
	s_nop 0
	v_lshl_add_u32 v0, s4, 6, v96
	v_ashrrev_i32_e32 v1, 31, v0
	v_lshl_add_u64 v[2:3], v[0:1], 2, s[92:93]
	v_mov_b32_e32 v1, v145
	s_movk_i32 s4, 0xff00
	v_lshl_add_u64 v[0:1], v[0:1], 2, s[94:95]
	s_mov_b32 s5, -1
	v_lshl_add_u64 v[0:1], v[0:1], 0, s[4:5]
	v_cndmask_b32_e32 v1, v1, v3, vcc
	v_cndmask_b32_e32 v0, v0, v2, vcc
	global_load_dword v0, v[0:1], off
	v_add_u32_e32 v1, 0x10c00, v101
	s_waitcnt vmcnt(0)
	ds_write_b32 v1, v0

; __global__ void __launch_bounds__(512) hymba_fwd(Args a) {
;     ...
;                 __syncthreads();
;                 { PrepIn cur; int u = wb; moba_prep_load(a, tid, u < 512 ? u : 0, cur);
;                   for (; u < 512; u += WG) { PrepIn nxt; moba_prep_unit(a, l, lds, tid, u, cur, nxt, (u + WG < 512) ? u + WG : u); cur = nxt; } }
;                 { HIn cur; int u = (wb + 160) % WG;     hgrn_load<false>(a, tid, u < 1024 ? u : 0, cur);
;                   for (; u < 1024; u += WG) { HIn nxt; hgrn_stage1_unit(a, l, lds, tid, u, cur, nxt, (u + WG < 1024) ? u + WG : u); cur = nxt; } }
.LBB0_424:
	s_or_b64 exec, exec, s[14:15]
	v_readlane_b32 s4, v245, 32
	v_readlane_b32 s5, v245, 33
	s_andn2_b64 vcc, exec, s[4:5]
	v_lshlrev_b32_e32 v124, 5, v96
	v_ashrrev_i32_e32 v97, 31, v96
	s_waitcnt lgkmcnt(0)
	s_barrier
	s_cmp_lg_u32 s99, 0
	s_cbranch_scc1 .Lx3_no
	s_bitcmp1_b32 s2, 3
	s_cbranch_scc0 .Lx3_no
	s_cmp_eq_u32 s3, 0x100
	s_cbranch_scc0 .Lx3_no
	s_mov_b32 s99, 1
	s_branch .LBB0_435
.Lx3_no:
	s_cbranch_vccnz .LBB0_435
	v_ashrrev_i32_e32 v98, 1, v96
	v_lshlrev_b32_e32 v196, 6, v96
	v_add_u32_e32 v196, 0x11000, v196
	v_and_b32_e32 v199, 63, v96
	v_lshrrev_b32_e32 v198, 6, v96
	v_lshlrev_b32_e32 v197, 4, v199
	v_lshl_or_b32 v197, v198, 12, v197
	v_add_u32_e32 v197, 0x11000, v197
	v_lshrrev_b32_e32 v201, 3, v199
	v_and_b32_e32 v200, 7, v199
	v_lshlrev_b32_e32 v200, 4, v200
	v_lshl_or_b32 v200, v201, 13, v200
	v_lshlrev_b32_e32 v199, 4, v199
	v_add_u32_e32 v201, 0x10000, v200
	v_add_u32_e32 v202, 0x20000, v200
	v_add_u32_e32 v203, 0x30000, v200
	v_readlane_b32 s4, v244, 8
	v_ashrrev_i32_e32 v99, 31, v98
	v_readlane_b32 s5, v244, 9
	v_and_b32_e32 v0, 32, v124
	v_lshlrev_b32_e32 v144, 1, v0
	v_lshl_add_u64 v[2:3], v[98:99], 0, s[4:5]
	v_readlane_b32 s4, v245, 34
	v_readlane_b32 s5, v245, 35
	v_and_b32_e32 v1, 1, v96
	v_lshlrev_b32_e32 v100, 5, v1
	v_lshl_add_u64 v[4:5], v[2:3], 0, s[4:5]
	v_readlane_b32 s4, v245, 40
	v_lshlrev_b64 v[6:7], 6, v[4:5]
	v_readlane_b32 s5, v245, 41
	v_lshlrev_b64 v[2:3], 7, v[2:3]
	v_cmp_eq_u32_e64 s[44:45], 0, v1
	v_lshl_add_u64 v[6:7], s[4:5], 0, v[6:7]
	v_readlane_b32 s4, v245, 38
	v_readlane_b32 s5, v245, 39
	global_load_dwordx4 v[48:51], v[6:7], off offset:48
	global_load_dwordx4 v[52:55], v[6:7], off offset:16
	global_load_dwordx4 v[56:59], v[6:7], off
	global_load_dwordx4 v[60:63], v[6:7], off offset:32
	v_lshl_add_u64 v[2:3], s[4:5], 0, v[2:3]
	v_lshl_add_u64 v[2:3], v[2:3], 0, v[144:145]
	v_readlane_b32 s4, v245, 36
	global_load_dwordx4 v[64:67], v[2:3], off offset:48
	global_load_dwordx4 v[68:71], v[2:3], off offset:32
	global_load_dwordx4 v[72:75], v[2:3], off offset:16
	global_load_dwordx4 v[76:79], v[2:3], off
	v_lshlrev_b64 v[2:3], 13, v[4:5]
	v_readlane_b32 s5, v245, 37
	v_lshrrev_b32_e32 v4, 5, v98
	v_cmp_gt_i32_e64 s[46:47], 64, v96
	v_lshl_add_u64 v[2:3], s[4:5], 0, v[2:3]
	v_lshl_add_u64 v[2:3], v[2:3], 0, v[144:145]
	global_load_dwordx4 v[80:83], v[2:3], off offset:48
	global_load_dwordx4 v[84:87], v[2:3], off offset:32
	global_load_dwordx4 v[88:91], v[2:3], off offset:16
	global_load_dwordx4 v[92:95], v[2:3], off
	s_add_i32 s4, 0, 0x10c00
	v_lshlrev_b32_e32 v2, 7, v1
	v_add_u32_e32 v125, s4, v2
	s_movk_i32 s4, 0x104
	v_add_u32_e32 v1, 0, v2
	v_mul_lo_u32 v2, v98, s4
	v_readlane_b32 s4, v244, 50
	v_and_b32_e32 v3, 63, v96
	v_lshlrev_b32_e32 v3, 2, v3
	v_lshl_add_u32 v126, v96, 2, s4
	s_movk_i32 s4, 0x2080
	v_mul_lo_u32 v4, v4, s4
	v_add3_u32 v127, v4, v3, 0
	v_lshlrev_b32_e32 v102, 1, v0
	v_add_u32_e32 v128, v1, v2
	v_readlane_b32 s5, v245, 44
	s_waitcnt vmcnt(11)
	v_mov_b32_e32 v105, v51
	s_waitcnt vmcnt(10)
	v_mov_b32_e32 v104, v55
	s_branch .LBB0_427

; template <bool NEEDQ>
; __device__ __forceinline__ void hgrn_load(const Args& a, int tid, int u, HIn& r) {
;     const int bh = u >> 5, c = u & 31, b = bh >> 2, hh = bh & 3; const size_t row0 = (size_t)b * SEQ + c * 64;
; #pragma unroll
;     for (int ii = 0; ii < 2; ++ii) { const int cid = tid + 512 * ii, t = cid >> 4, d0 = (cid & 15) * 8;
;         const bf16_t* p = (const bf16_t*)(a.ws + WS_PROJ) + (row0 + t) * NCOL + hh * 128 + d0;
;         r.f[ii] = *(const u32x4*)(p + CFH); r.v[ii] = *(const u32x4*)(p + CIH); if (NEEDQ) r.q[ii] = *(const u32x4*)(p + CQH); }
; }
; __global__ void __launch_bounds__(512) hymba_fwd(Args a) {
;     ...
;                 { HIn cur; int u = (wb + 160) % WG;     hgrn_load<false>(a, tid, u < 1024 ? u : 0, cur);
;                   for (; u < 1024; u += WG) { HIn nxt; hgrn_stage1_unit(a, l, lds, tid, u, cur, nxt, (u + WG < 1024) ? u + WG : u); cur = nxt; } }
.LBB0_435:
	s_cmp_eq_u32 s99, 2
	s_cbranch_scc1 .Lx3_end
	v_readlane_b32 s4, v244, 37
	v_readlane_b32 s5, v244, 38
	s_andn2_b64 vcc, exec, s[4:5]
	s_cbranch_vccnz .LBB0_448
	v_lshlrev_b32_e32 v0, 3, v96
	v_and_b32_e32 v16, 0x78, v0
	v_add_u32_e32 v0, 0x200, v96
	v_ashrrev_i32_e32 v34, 4, v0
	v_readlane_b32 s4, v244, 39
	v_ashrrev_i32_e32 v35, 31, v34
	v_readlane_b32 s5, v244, 40
	v_readlane_b32 s8, v244, 42
	v_readlane_b32 s9, v244, 43
	v_lshl_add_u64 v[0:1], s[4:5], 0, v[34:35]
	v_lshlrev_b64 v[0:1], 13, v[0:1]
	v_lshl_add_u64 v[0:1], s[8:9], 0, v[0:1]
	v_lshlrev_b32_e32 v144, 1, v16
	v_lshl_add_u64 v[0:1], v[0:1], 0, v[144:145]
	v_ashrrev_i32_e32 v32, 4, v96
	v_add_co_u32_e32 v4, vcc, s26, v0
	v_ashrrev_i32_e32 v33, 31, v32
	s_nop 0
	v_addc_co_u32_e32 v5, vcc, 0, v1, vcc
	global_load_dwordx4 v[0:3], v[4:5], off offset:3072
	global_load_dwordx4 v[8:11], v[4:5], off offset:2048
	v_lshl_add_u64 v[4:5], s[4:5], 0, v[32:33]
	v_lshlrev_b64 v[4:5], 13, v[4:5]
	v_lshl_add_u64 v[4:5], s[8:9], 0, v[4:5]
	v_lshl_add_u64 v[4:5], v[4:5], 0, v[144:145]
	v_add_co_u32_e32 v12, vcc, s26, v4
	s_add_i32 s4, 0, 0x1a000
	s_nop 0
	v_addc_co_u32_e32 v13, vcc, 0, v5, vcc
	global_load_dwordx4 v[4:7], v[12:13], off offset:3072
	s_nop 0
	global_load_dwordx4 v[12:15], v[12:13], off offset:2048
	v_lshlrev_b32_e32 v17, 2, v16
	v_add_u32_e32 v64, s4, v17
	v_add_u32_e32 v65, 0, v17
	v_and_b32_e32 v17, 0xfffffe00, v124
	v_add_u32_e32 v66, v65, v17
	v_and_b32_e32 v17, 0x7f, v96
	v_ashrrev_i32_e32 v18, 7, v96
	v_lshl_add_u32 v67, v17, 2, 0
	v_and_b32_e32 v17, 15, v96
	v_lshl_add_u32 v68, v18, 13, v67
	v_cmp_lt_i32_e64 s[44:45], 0, v18
	v_cmp_lt_i32_e64 s[46:47], 1, v18
	v_cmp_lt_i32_e64 s[48:49], 2, v18
	v_lshrrev_b32_e32 v18, 2, v96
	v_lshlrev_b32_e32 v24, 3, v17
	v_bfe_u32 v25, v96, 2, 4
	v_sub_u32_e32 v19, v65, v144
	v_lshlrev_b32_e32 v20, 9, v32
	v_mul_lo_u32 v21, v32, s27
	v_lshlrev_b32_e32 v22, 9, v34
	v_mul_lo_u32 v23, v34, s27
	v_and_b32_e32 v18, 12, v18
	v_and_b32_e32 v69, 24, v24
	v_mul_u32_u24_e32 v71, 0x120, v25
	v_mad_u32_u24 v72, v25, s27, 0
	v_or_b32_e32 v25, 0x60, v24
	v_or_b32_e32 v24, 0xe0, v24
	v_add_u32_e32 v70, 0, v69
	v_lshlrev_b32_e32 v73, 3, v17
	v_lshlrev_b32_e32 v144, 1, v16
	v_add_u32_e32 v74, v65, v20
	v_add_u32_e32 v75, v19, v21
	v_add_u32_e32 v76, v65, v22
	v_add_u32_e32 v77, v19, v23
	v_add_u32_e32 v78, v72, v25
	v_add_u32_e32 v79, v72, v24
	v_and_b32_e32 v36, 4, v18
	v_and_b32_e32 v25, 8, v18
	v_lshlrev_b32_e32 v36, 1, v36
	v_lshl_or_b32 v36, v25, 5, v36
	v_readlane_b32 s8, v244, 41
	s_branch .LBB0_438

; __global__ void __launch_bounds__(512) hymba_fwd(Args a) {
;     ...
;                   for (; u < 1024; u += WG) { HIn nxt; hgrn_stage1_unit(a, l, lds, tid, u, cur, nxt, (u + WG < 1024) ? u + WG : u); cur = nxt; } }
;                 __syncthreads();
.LBB0_448:
	s_cmp_eq_u32 s99, 1
	s_cbranch_scc1 .Lx3_ret
	s_waitcnt lgkmcnt(0)
	s_barrier

; __global__ void __launch_bounds__(512) hymba_fwd(Args a) {
;     ...
;                 { PrepIn cur; int u = wb; moba_prep_load(a, tid, u < 512 ? u : 0, cur);
;                   for (; u < 512; u += WG) { PrepIn nxt; moba_prep_unit(a, l, lds, tid, u, cur, nxt, (u + WG < 512) ? u + WG : u); cur = nxt; } }
;                 { HIn cur; int u = (wb + 160) % WG;     hgrn_load<false>(a, tid, u < 1024 ? u : 0, cur);
;                   for (; u < 1024; u += WG) { HIn nxt; hgrn_stage1_unit(a, l, lds, tid, u, cur, nxt, (u + WG < 1024) ? u + WG : u); cur = nxt; } }
;                 __syncthreads();
.Lx3_ret:
	s_waitcnt vmcnt(0)
	s_mov_b32 s99, 2
	s_branch .Lx3_reload
.Lx3_end:
	s_waitcnt vmcnt(0)
	s_branch .LBB0_448
